# init row pass: looped two-rows-in-flight fast path (two load register sets, counted waits) for the 512-workgroup grid
# speedup vs baseline: 1.0024x; 1.0009x over previous
.LBB0_204:
	s_or_b64 exec, exec, s[0:1]
	s_lshl_b32 s8, s64, 2
	s_mov_b32 s0, s8
	v_ashrrev_i32_e32 v0, 6, v42
	v_writelane_b32 v252, s0, 26
	v_add_u32_e32 v6, s8, v0
	s_nop 0
	v_writelane_b32 v252, s1, 27
	s_movk_i32 s0, 0x4000
	v_cmp_gt_i32_e32 vcc, s0, v6
	s_and_saveexec_b64 s[8:9], vcc
	s_cbranch_execz .LBB0_209
	v_mbcnt_lo_u32_b32 v1, -1, 0
	v_mbcnt_hi_u32_b32 v1, -1, v1
	v_and_b32_e32 v2, 64, v1
	v_add_u32_e32 v2, 64, v2
	v_xor_b32_e32 v3, 32, v1
	v_cmp_lt_i32_e32 vcc, v3, v2
	v_readlane_b32 s12, v252, 2
	v_readlane_b32 s13, v252, 3
	v_cndmask_b32_e32 v3, v1, v3, vcc
	v_lshlrev_b32_e32 v7, 2, v3
	v_xor_b32_e32 v3, 16, v1
	v_cmp_lt_i32_e32 vcc, v3, v2
	v_readlane_b32 s14, v252, 4
	v_readlane_b32 s15, v252, 5
	v_cndmask_b32_e32 v3, v1, v3, vcc
	v_lshlrev_b32_e32 v8, 2, v3
	v_xor_b32_e32 v3, 8, v1
	v_cmp_lt_i32_e32 vcc, v3, v2
	v_readlane_b32 s12, v252, 26
	s_mov_b32 s14, s12
	v_cndmask_b32_e32 v3, v1, v3, vcc
	v_lshlrev_b32_e32 v9, 2, v3
	v_xor_b32_e32 v3, 4, v1
	v_cmp_lt_i32_e32 vcc, v3, v2
	s_ashr_i32 s15, s12, 31
	v_and_b32_e32 v13, 63, v42
	v_cndmask_b32_e32 v3, v1, v3, vcc
	v_lshlrev_b32_e32 v10, 2, v3
	v_xor_b32_e32 v3, 2, v1
	v_cmp_lt_i32_e32 vcc, v3, v2
	v_readlane_b32 s18, v252, 8
	v_readlane_b32 s16, v252, 6
	v_cndmask_b32_e32 v3, v1, v3, vcc
	v_lshlrev_b32_e32 v11, 2, v3
	v_xor_b32_e32 v3, 1, v1
	v_cmp_lt_i32_e32 vcc, v3, v2
	v_readlane_b32 s17, v252, 7
	s_lshl_b32 s10, s18, 2
	v_cndmask_b32_e32 v1, v1, v3, vcc
	v_lshlrev_b32_e32 v12, 2, v1
	v_ashrrev_i32_e32 v1, 31, v0
	v_lshl_add_u64 v[4:5], v[0:1], 0, s[14:15]
	v_mov_b64_e32 v[0:1], 0x3dc0000
	v_lshl_add_u64 v[0:1], v[4:5], 2, v[0:1]
	v_lshlrev_b64 v[2:3], 11, v[4:5]
	v_lshlrev_b64 v[4:5], 12, v[4:5]
	v_readlane_b32 s13, v252, 27
	v_lshl_or_b32 v4, v13, 4, v4
	v_readlane_b32 s19, v252, 9
	v_writelane_b32 v252, s12, 26
	s_ashr_i32 s11, s10, 31
	v_lshl_add_u64 v[4:5], s[80:81], 0, v[4:5]
	s_mov_b64 s[16:17], 0xc00
	v_cmp_eq_u32_e64 s[0:1], 0, v13
	v_writelane_b32 v252, s13, 27
	s_lshl_b64 s[12:13], s[10:11], 2
	v_lshl_or_b32 v2, v13, 3, v2
	s_lshl_b64 s[14:15], s[10:11], 11
	v_lshl_add_u64 v[4:5], v[4:5], 0, s[16:17]
	s_lshl_b64 s[16:17], s[10:11], 12
	s_mov_b64 s[18:19], 0
	s_mov_b32 s11, 0x1dc0000
	v_mov_b32_e32 v13, 0x358637bd
	s_mov_b32 s22, 0x800000
	s_movk_i32 s23, 0x3fff
	s_cmpk_eq_u32 s10, 0x800
	s_cbranch_scc1 .Lrp_fast
	s_branch .LBB0_207

.Lrp_fast:
	global_load_dwordx4 v[14:17], v[4:5], off offset:-3072
	global_load_dwordx4 v[18:21], v[4:5], off offset:-2048
	global_load_dwordx4 v[22:25], v[4:5], off offset:-1024
	global_load_dwordx4 v[26:29], v[4:5], off
	v_lshl_add_u64 v[4:5], v[4:5], 0, s[16:17]
	global_load_dwordx4 v[64:67], v[4:5], off offset:-3072
	global_load_dwordx4 v[68:71], v[4:5], off offset:-2048
	global_load_dwordx4 v[72:75], v[4:5], off offset:-1024
	global_load_dwordx4 v[76:79], v[4:5], off
	v_lshl_add_u64 v[4:5], v[4:5], 0, s[16:17]
	s_movk_i32 s101, 3
	s_waitcnt vmcnt(4)
.Lrp_loop:
	v_mul_f32_e32 v30, v15, v15
	v_mul_f32_e32 v31, v19, v19
	v_mul_f32_e32 v32, v23, v23
	v_fmac_f32_e32 v30, v14, v14
	v_fmac_f32_e32 v31, v18, v18
	v_mul_f32_e32 v33, v27, v27
	v_fmac_f32_e32 v32, v22, v22
	v_fmac_f32_e32 v30, v16, v16
	v_fmac_f32_e32 v31, v20, v20
	v_fmac_f32_e32 v33, v26, v26
	v_fmac_f32_e32 v32, v24, v24
	v_fmac_f32_e32 v30, v17, v17
	v_fmac_f32_e32 v31, v21, v21
	v_fmac_f32_e32 v33, v28, v28
	v_fmac_f32_e32 v32, v25, v25
	v_add_f32_e32 v30, v30, v31
	v_fmac_f32_e32 v33, v29, v29
	v_add_f32_e32 v30, v30, v32
	v_add_f32_e32 v30, v30, v33
	v_mov_b32_e32 v100, v30
	v_mov_b32_e32 v101, v30
	v_cvt_pk_bf16_f32 v14, v14, v15
	v_cvt_pk_bf16_f32 v15, v16, v17
	v_permlane32_swap_b32_e32 v100, v101
	v_lshl_add_u64 v[30:31], s[2:3], 0, v[2:3]
	v_add_co_u32_e32 v30, vcc, s11, v30
	v_add_f32_e32 v102, v100, v101
	v_mov_b32_e32 v103, v102
	v_addc_co_u32_e32 v31, vcc, 0, v31, vcc
	global_store_dwordx2 v[30:31], v[14:15], off
	v_permlane16_swap_b32_e32 v102, v103
	v_cvt_pk_bf16_f32 v14, v18, v19
	v_cvt_pk_bf16_f32 v15, v20, v21
	v_add_f32_e32 v104, v102, v103
	global_store_dwordx2 v[30:31], v[14:15], off offset:512
	v_cvt_pk_bf16_f32 v16, v22, v23
	v_cvt_pk_bf16_f32 v17, v24, v25
	v_add_f32_dpp v105, v104, v104 row_shl:8 row_mask:0xf bank_mask:0xf
	global_store_dwordx2 v[30:31], v[16:17], off offset:1024
	v_cvt_pk_bf16_f32 v16, v26, v27
	v_cvt_pk_bf16_f32 v17, v28, v29
	v_add_f32_dpp v106, v105, v105 row_shl:4 row_mask:0xf bank_mask:0xf
	global_store_dwordx2 v[30:31], v[16:17], off offset:1536
	s_nop 1
	v_add_f32_dpp v107, v106, v106 row_shl:2 row_mask:0xf bank_mask:0xf
	s_nop 1
	v_add_f32_dpp v14, v107, v107 row_shl:1 row_mask:0xf bank_mask:0xf
	s_and_saveexec_b64 s[20:21], s[0:1]
	v_fmamk_f32 v14, v14, 0x3a800000, v13
	v_mul_f32_e32 v15, 0x4b800000, v14
	v_cmp_gt_f32_e32 vcc, s22, v14
	s_nop 1
	v_cndmask_b32_e32 v14, v14, v15, vcc
	v_rsq_f32_e32 v16, v14
	v_lshl_add_u64 v[14:15], s[2:3], 0, v[0:1]
	v_mul_f32_e32 v17, 0x45800000, v16
	v_cndmask_b32_e32 v16, v16, v17, vcc
	global_store_dword v[14:15], v16, off
	s_or_b64 exec, exec, s[20:21]
	v_lshl_add_u64 v[0:1], v[0:1], 0, s[12:13]
	v_lshl_add_u64 v[2:3], v[2:3], 0, s[14:15]
	global_load_dwordx4 v[14:17], v[4:5], off offset:-3072
	global_load_dwordx4 v[18:21], v[4:5], off offset:-2048
	global_load_dwordx4 v[22:25], v[4:5], off offset:-1024
	global_load_dwordx4 v[26:29], v[4:5], off
	v_lshl_add_u64 v[4:5], v[4:5], 0, s[16:17]
	s_waitcnt vmcnt(9)
	v_mul_f32_e32 v30, v65, v65
	v_mul_f32_e32 v31, v69, v69
	v_mul_f32_e32 v32, v73, v73
	v_fmac_f32_e32 v30, v64, v64
	v_fmac_f32_e32 v31, v68, v68
	v_mul_f32_e32 v33, v77, v77
	v_fmac_f32_e32 v32, v72, v72
	v_fmac_f32_e32 v30, v66, v66
	v_fmac_f32_e32 v31, v70, v70
	v_fmac_f32_e32 v33, v76, v76
	v_fmac_f32_e32 v32, v74, v74
	v_fmac_f32_e32 v30, v67, v67
	v_fmac_f32_e32 v31, v71, v71
	v_fmac_f32_e32 v33, v78, v78
	v_fmac_f32_e32 v32, v75, v75
	v_add_f32_e32 v30, v30, v31
	v_fmac_f32_e32 v33, v79, v79
	v_add_f32_e32 v30, v30, v32
	v_add_f32_e32 v30, v30, v33
	v_mov_b32_e32 v100, v30
	v_mov_b32_e32 v101, v30
	v_cvt_pk_bf16_f32 v64, v64, v65
	v_cvt_pk_bf16_f32 v65, v66, v67
	v_permlane32_swap_b32_e32 v100, v101
	v_lshl_add_u64 v[30:31], s[2:3], 0, v[2:3]
	v_add_co_u32_e32 v30, vcc, s11, v30
	v_add_f32_e32 v102, v100, v101
	v_mov_b32_e32 v103, v102
	v_addc_co_u32_e32 v31, vcc, 0, v31, vcc
	global_store_dwordx2 v[30:31], v[64:65], off
	v_permlane16_swap_b32_e32 v102, v103
	v_cvt_pk_bf16_f32 v64, v68, v69
	v_cvt_pk_bf16_f32 v65, v70, v71
	v_add_f32_e32 v104, v102, v103
	global_store_dwordx2 v[30:31], v[64:65], off offset:512
	v_cvt_pk_bf16_f32 v66, v72, v73
	v_cvt_pk_bf16_f32 v67, v74, v75
	v_add_f32_dpp v105, v104, v104 row_shl:8 row_mask:0xf bank_mask:0xf
	global_store_dwordx2 v[30:31], v[66:67], off offset:1024
	v_cvt_pk_bf16_f32 v66, v76, v77
	v_cvt_pk_bf16_f32 v67, v78, v79
	v_add_f32_dpp v106, v105, v105 row_shl:4 row_mask:0xf bank_mask:0xf
	global_store_dwordx2 v[30:31], v[66:67], off offset:1536
	s_nop 1
	v_add_f32_dpp v107, v106, v106 row_shl:2 row_mask:0xf bank_mask:0xf
	s_nop 1
	v_add_f32_dpp v64, v107, v107 row_shl:1 row_mask:0xf bank_mask:0xf
	s_and_saveexec_b64 s[20:21], s[0:1]
	v_fmamk_f32 v64, v64, 0x3a800000, v13
	v_mul_f32_e32 v65, 0x4b800000, v64
	v_cmp_gt_f32_e32 vcc, s22, v64
	s_nop 1
	v_cndmask_b32_e32 v64, v64, v65, vcc
	v_rsq_f32_e32 v66, v64
	v_lshl_add_u64 v[64:65], s[2:3], 0, v[0:1]
	v_mul_f32_e32 v67, 0x45800000, v66
	v_cndmask_b32_e32 v66, v66, v67, vcc
	global_store_dword v[64:65], v66, off
	s_or_b64 exec, exec, s[20:21]
	v_lshl_add_u64 v[0:1], v[0:1], 0, s[12:13]
	v_lshl_add_u64 v[2:3], v[2:3], 0, s[14:15]
	global_load_dwordx4 v[64:67], v[4:5], off offset:-3072
	global_load_dwordx4 v[68:71], v[4:5], off offset:-2048
	global_load_dwordx4 v[72:75], v[4:5], off offset:-1024
	global_load_dwordx4 v[76:79], v[4:5], off
	v_lshl_add_u64 v[4:5], v[4:5], 0, s[16:17]
	s_waitcnt vmcnt(9)
	s_sub_u32 s101, s101, 1
	s_cmp_lg_u32 s101, 0
	s_cbranch_scc1 .Lrp_loop
	v_mul_f32_e32 v30, v15, v15
	v_mul_f32_e32 v31, v19, v19
	v_mul_f32_e32 v32, v23, v23
	v_fmac_f32_e32 v30, v14, v14
	v_fmac_f32_e32 v31, v18, v18
	v_mul_f32_e32 v33, v27, v27
	v_fmac_f32_e32 v32, v22, v22
	v_fmac_f32_e32 v30, v16, v16
	v_fmac_f32_e32 v31, v20, v20
	v_fmac_f32_e32 v33, v26, v26
	v_fmac_f32_e32 v32, v24, v24
	v_fmac_f32_e32 v30, v17, v17
	v_fmac_f32_e32 v31, v21, v21
	v_fmac_f32_e32 v33, v28, v28
	v_fmac_f32_e32 v32, v25, v25
	v_add_f32_e32 v30, v30, v31
	v_fmac_f32_e32 v33, v29, v29
	v_add_f32_e32 v30, v30, v32
	v_add_f32_e32 v30, v30, v33
	v_mov_b32_e32 v100, v30
	v_mov_b32_e32 v101, v30
	v_cvt_pk_bf16_f32 v14, v14, v15
	v_cvt_pk_bf16_f32 v15, v16, v17
	v_permlane32_swap_b32_e32 v100, v101
	v_lshl_add_u64 v[30:31], s[2:3], 0, v[2:3]
	v_add_co_u32_e32 v30, vcc, s11, v30
	v_add_f32_e32 v102, v100, v101
	v_mov_b32_e32 v103, v102
	v_addc_co_u32_e32 v31, vcc, 0, v31, vcc
	global_store_dwordx2 v[30:31], v[14:15], off
	v_permlane16_swap_b32_e32 v102, v103
	v_cvt_pk_bf16_f32 v14, v18, v19
	v_cvt_pk_bf16_f32 v15, v20, v21
	v_add_f32_e32 v104, v102, v103
	global_store_dwordx2 v[30:31], v[14:15], off offset:512
	v_cvt_pk_bf16_f32 v16, v22, v23
	v_cvt_pk_bf16_f32 v17, v24, v25
	v_add_f32_dpp v105, v104, v104 row_shl:8 row_mask:0xf bank_mask:0xf
	global_store_dwordx2 v[30:31], v[16:17], off offset:1024
	v_cvt_pk_bf16_f32 v16, v26, v27
	v_cvt_pk_bf16_f32 v17, v28, v29
	v_add_f32_dpp v106, v105, v105 row_shl:4 row_mask:0xf bank_mask:0xf
	global_store_dwordx2 v[30:31], v[16:17], off offset:1536
	s_nop 1
	v_add_f32_dpp v107, v106, v106 row_shl:2 row_mask:0xf bank_mask:0xf
	s_nop 1
	v_add_f32_dpp v14, v107, v107 row_shl:1 row_mask:0xf bank_mask:0xf
	s_and_saveexec_b64 s[20:21], s[0:1]
	v_fmamk_f32 v14, v14, 0x3a800000, v13
	v_mul_f32_e32 v15, 0x4b800000, v14
	v_cmp_gt_f32_e32 vcc, s22, v14
	s_nop 1
	v_cndmask_b32_e32 v14, v14, v15, vcc
	v_rsq_f32_e32 v16, v14
	v_lshl_add_u64 v[14:15], s[2:3], 0, v[0:1]
	v_mul_f32_e32 v17, 0x45800000, v16
	v_cndmask_b32_e32 v16, v16, v17, vcc
	global_store_dword v[14:15], v16, off
	s_or_b64 exec, exec, s[20:21]
	v_lshl_add_u64 v[0:1], v[0:1], 0, s[12:13]
	v_lshl_add_u64 v[2:3], v[2:3], 0, s[14:15]
	s_waitcnt vmcnt(5)
	v_mul_f32_e32 v30, v65, v65
	v_mul_f32_e32 v31, v69, v69
	v_mul_f32_e32 v32, v73, v73
	v_fmac_f32_e32 v30, v64, v64
	v_fmac_f32_e32 v31, v68, v68
	v_mul_f32_e32 v33, v77, v77
	v_fmac_f32_e32 v32, v72, v72
	v_fmac_f32_e32 v30, v66, v66
	v_fmac_f32_e32 v31, v70, v70
	v_fmac_f32_e32 v33, v76, v76
	v_fmac_f32_e32 v32, v74, v74
	v_fmac_f32_e32 v30, v67, v67
	v_fmac_f32_e32 v31, v71, v71
	v_fmac_f32_e32 v33, v78, v78
	v_fmac_f32_e32 v32, v75, v75
	v_add_f32_e32 v30, v30, v31
	v_fmac_f32_e32 v33, v79, v79
	v_add_f32_e32 v30, v30, v32
	v_add_f32_e32 v30, v30, v33
	v_mov_b32_e32 v100, v30
	v_mov_b32_e32 v101, v30
	v_cvt_pk_bf16_f32 v64, v64, v65
	v_cvt_pk_bf16_f32 v65, v66, v67
	v_permlane32_swap_b32_e32 v100, v101
	v_lshl_add_u64 v[30:31], s[2:3], 0, v[2:3]
	v_add_co_u32_e32 v30, vcc, s11, v30
	v_add_f32_e32 v102, v100, v101
	v_mov_b32_e32 v103, v102
	v_addc_co_u32_e32 v31, vcc, 0, v31, vcc
	global_store_dwordx2 v[30:31], v[64:65], off
	v_permlane16_swap_b32_e32 v102, v103
	v_cvt_pk_bf16_f32 v64, v68, v69
	v_cvt_pk_bf16_f32 v65, v70, v71
	v_add_f32_e32 v104, v102, v103
	global_store_dwordx2 v[30:31], v[64:65], off offset:512
	v_cvt_pk_bf16_f32 v66, v72, v73
	v_cvt_pk_bf16_f32 v67, v74, v75
	v_add_f32_dpp v105, v104, v104 row_shl:8 row_mask:0xf bank_mask:0xf
	global_store_dwordx2 v[30:31], v[66:67], off offset:1024
	v_cvt_pk_bf16_f32 v66, v76, v77
	v_cvt_pk_bf16_f32 v67, v78, v79
	v_add_f32_dpp v106, v105, v105 row_shl:4 row_mask:0xf bank_mask:0xf
	global_store_dwordx2 v[30:31], v[66:67], off offset:1536
	s_nop 1
	v_add_f32_dpp v107, v106, v106 row_shl:2 row_mask:0xf bank_mask:0xf
	s_nop 1
	v_add_f32_dpp v64, v107, v107 row_shl:1 row_mask:0xf bank_mask:0xf
	s_and_saveexec_b64 s[20:21], s[0:1]
	v_fmamk_f32 v64, v64, 0x3a800000, v13
	v_mul_f32_e32 v65, 0x4b800000, v64
	v_cmp_gt_f32_e32 vcc, s22, v64
	s_nop 1
	v_cndmask_b32_e32 v64, v64, v65, vcc
	v_rsq_f32_e32 v66, v64
	v_lshl_add_u64 v[64:65], s[2:3], 0, v[0:1]
	v_mul_f32_e32 v67, 0x45800000, v66
	v_cndmask_b32_e32 v66, v66, v67, vcc
	global_store_dword v[64:65], v66, off
	s_or_b64 exec, exec, s[20:21]
	v_lshl_add_u64 v[0:1], v[0:1], 0, s[12:13]
	v_lshl_add_u64 v[2:3], v[2:3], 0, s[14:15]
